# final stack plus non-temporal hint on P3's x row loads (the input's last use)
# baseline (speedup 1.0000x reference)
; #define GAS __attribute__((address_space(1)))
; __device__ __forceinline__ float bflo(unsigned w) { return __uint_as_float(w << 16); }
; __device__ __forceinline__ float bfhi(unsigned w) { return __uint_as_float(w & 0xffff0000u); }
; __device__ __forceinline__ float sigmf(float x) { return __builtin_amdgcn_rcpf(1.0f + __expf(-x)); }
; __device__ __forceinline__ float dot4(f32x4 a, f32x4 b) { return (a[0] * b[0] + a[1] * b[1]) + (a[2] * b[2] + a[3] * b[3]); }
;     ...
;         else { const GAS f32x4* rp = (const GAS f32x4*)xrow(a, r) + lane;
; #pragma unroll
;             for (int j = 0; j < 8; ++j) v[j] = rp[64 * j]; }
;         if (MODE != 0) {
;             const GAS v2u* tp = (const GAS v2u*)(T + (size_t)r * D) + lane;
;             f32x4 t[8]; float ss = 0.f;
;             if (TSRC != 0 && r >= NP) {
;                 const GAS f32x4* sp = (const GAS f32x4*)(WSP(float, WS_SLAB) + (size_t)(r - NP) * D) + lane;
; #pragma unroll
;                 for (int j = 0; j < 8; ++j) t[j] = sp[64 * j];
;                 _Pragma("unroll 1") for (int s = 1; s < nslab; ++s) { sp += (size_t)NS * D / 4;
; #pragma unroll
;                     for (int j = 0; j < 8; ++j) t[j] += sp[64 * j]; }
;                 if (TSRC == 2) { const GAS v2u* pp = (const GAS v2u*)(PUP + (size_t)r * D) + lane;
; #pragma unroll
;                     for (int j = 0; j < 8; ++j) { const v2u pw = pp[64 * j]; const f32x4 p = (f32x4){bflo(pw.x), bfhi(pw.x), bflo(pw.y), bfhi(pw.y)}; t[j] = (f32x4){sigmf(t[j][0]), sigmf(t[j][1]), sigmf(t[j][2]), sigmf(t[j][3])} * p; } }
; #pragma unroll
;                 for (int j = 0; j < 8; ++j) ss += dot4(t[j], t[j]);
;             } else {
; #pragma unroll
;                 for (int j = 0; j < 8; ++j) { const v2u tw = tp[64 * j]; t[j] = (f32x4){bflo(tw.x), bfhi(tw.x), bflo(tw.y), bfhi(tw.y)}; ss += dot4(t[j], t[j]); }
.LBB0_272:
	s_add_i32 s10, s8, 0xffffe000
	s_ashr_i32 s9, s8, 31
	s_cmpk_lt_i32 s8, 0x2000
	s_cselect_b32 s7, s9, 0
	s_cselect_b32 s6, s8, s10
	s_waitcnt lgkmcnt(0)
	s_cselect_b32 s13, s37, s39
	s_cselect_b32 s14, s36, s38
	s_lshl_b64 s[6:7], s[6:7], 13
	s_add_u32 s6, s14, s6
	s_addc_u32 s7, s13, s7
	v_lshl_add_u64 v[66:67], s[6:7], 0, v[130:131]
	v_add_co_u32_e32 v66, vcc, 0x1000, v66
	global_load_dwordx4 v[94:97], v130, s[6:7] nt
	global_load_dwordx4 v[90:93], v130, s[6:7] offset:1024 nt
	global_load_dwordx4 v[86:89], v130, s[6:7] offset:2048 nt
	global_load_dwordx4 v[82:85], v130, s[6:7] offset:3072 nt
	v_addc_co_u32_e32 v67, vcc, 0, v67, vcc
	global_load_dwordx4 v[78:81], v[66:67], off nt
	global_load_dwordx4 v[74:77], v[66:67], off offset:1024 nt
	global_load_dwordx4 v[70:73], v[66:67], off offset:2048 nt
	s_nop 0
	global_load_dwordx4 v[66:69], v[66:67], off offset:3072 nt
	s_lshl_b64 s[14:15], s[8:9], 11
	s_cmpk_gt_i32 s8, 0x1fff
	s_mov_b64 s[6:7], -1
	s_cbranch_scc1 .LBB0_274
	v_lshl_add_u64 v[98:99], s[14:15], 1, v[132:133]
	global_load_dwordx2 v[100:101], v[98:99], off
	global_load_dwordx2 v[102:103], v[98:99], off offset:512
	global_load_dwordx2 v[104:105], v[98:99], off offset:1024
	global_load_dwordx2 v[106:107], v[98:99], off offset:1536
	global_load_dwordx2 v[108:109], v[98:99], off offset:2048
	global_load_dwordx2 v[118:119], v[98:99], off offset:2560
	global_load_dwordx2 v[120:121], v[98:99], off offset:3072
	global_load_dwordx2 v[126:127], v[98:99], off offset:3584
	s_mov_b64 s[6:7], 0
	s_waitcnt vmcnt(0)
	v_and_b32_e32 v123, 0xffff0000, v100
	v_and_b32_e32 v125, 0xffff0000, v101
	v_and_b32_e32 v155, 0xffff0000, v103
	v_and_b32_e32 v154, 0xffff0000, v102
	v_lshlrev_b32_e32 v110, 16, v106
	v_lshlrev_b32_e32 v122, 16, v100
	v_lshlrev_b32_e32 v124, 16, v101
	v_lshlrev_b32_e32 v143, 16, v103
	v_lshlrev_b32_e32 v142, 16, v102
	v_lshlrev_b32_e32 v100, 16, v127
	v_and_b32_e32 v101, 0xffff0000, v127
	v_mul_f32_e32 v162, v125, v125
	v_mov_b32_e32 v127, v154
	v_mov_b32_e32 v129, v155
	v_pk_mul_f32 v[154:155], v[154:155], v[154:155]
	v_mul_f32_e32 v164, v123, v123
	v_mov_b32_e32 v163, v110
	v_mov_b32_e32 v165, v110
	v_and_b32_e32 v115, 0xffff0000, v104
	v_and_b32_e32 v117, 0xffff0000, v105
	v_and_b32_e32 v111, 0xffff0000, v106
	v_lshlrev_b32_e32 v112, 16, v107
	v_and_b32_e32 v113, 0xffff0000, v107
	v_and_b32_e32 v107, 0xffff0000, v109
	v_and_b32_e32 v106, 0xffff0000, v108
	v_and_b32_e32 v161, 0xffff0000, v119
	v_and_b32_e32 v160, 0xffff0000, v118
	v_lshlrev_b32_e32 v98, 16, v126
	v_and_b32_e32 v99, 0xffff0000, v126
	v_mov_b32_e32 v126, v142
	v_mov_b32_e32 v128, v143
	v_pk_fma_f32 v[172:173], v[124:125], v[124:125], v[162:163] op_sel_hi:[1,1,0]
	v_pk_fma_f32 v[142:143], v[142:143], v[142:143], v[154:155]
	v_pk_fma_f32 v[154:155], v[122:123], v[122:123], v[164:165] op_sel_hi:[1,1,0]
	v_lshlrev_b32_e32 v114, 16, v104
	v_lshlrev_b32_e32 v116, 16, v105
	v_lshlrev_b32_e32 v157, 16, v109
	v_lshlrev_b32_e32 v159, 16, v119
	v_lshlrev_b32_e32 v158, 16, v118
	v_lshlrev_b32_e32 v104, 16, v121
	v_and_b32_e32 v105, 0xffff0000, v121
	v_mul_f32_e32 v166, v115, v115
	v_mul_f32_e32 v168, v117, v117
	v_mov_b32_e32 v121, v107
	v_pk_mul_f32 v[170:171], v[106:107], v[106:107]
	v_mov_b32_e32 v107, v160
	v_mov_b32_e32 v109, v161
	v_pk_mul_f32 v[160:161], v[160:161], v[160:161]
	v_mov_b32_e32 v167, v98
	v_mov_b32_e32 v162, v154
	v_mov_b32_e32 v164, v172
	v_lshlrev_b32_e32 v156, 16, v108
	v_mul_f32_e32 v153, v111, v111
	v_mul_f32_e32 v176, v112, v112
	v_mul_f32_e32 v177, v113, v113
	v_mov_b32_e32 v119, v106
	v_mov_b32_e32 v106, v158
	v_mov_b32_e32 v108, v159
	v_pk_fma_f32 v[174:175], v[114:115], v[114:115], v[166:167] op_sel_hi:[1,1,0]
	v_pk_fma_f32 v[168:169], v[116:117], v[116:117], v[168:169] op_sel_hi:[1,1,0]
	v_pk_fma_f32 v[158:159], v[158:159], v[158:159], v[160:161]
	v_pk_add_f32 v[154:155], v[154:155], v[172:173]
	v_pk_add_f32 v[142:143], v[142:143], v[142:143] op_sel:[0,1] op_sel_hi:[1,0]
	v_pk_mul_f32 v[160:161], v[162:163], v[164:165]
	v_mov_b32_e32 v175, v176
	v_mov_b32_e32 v169, v177
	v_mov_b32_e32 v143, v153
	v_mov_b32_e32 v155, v161
	v_pk_add_f32 v[162:163], v[174:175], v[168:169]
	v_pk_add_f32 v[142:143], v[154:155], v[142:143]
	v_lshlrev_b32_e32 v102, 16, v120
	v_and_b32_e32 v103, 0xffff0000, v120
	v_mov_b32_e32 v118, v156
	v_mov_b32_e32 v120, v157
	v_pk_fma_f32 v[156:157], v[156:157], v[156:157], v[170:171]
	v_pk_add_f32 v[142:143], v[142:143], v[162:163]
	v_pk_add_f32 v[156:157], v[156:157], v[156:157] op_sel:[0,1] op_sel_hi:[1,0]
	v_pk_add_f32 v[142:143], v[142:143], v[142:143] op_sel:[0,1] op_sel_hi:[1,0]
	v_mov_b32_e32 v154, v156
	v_mov_b32_e32 v166, v142
	v_mov_b32_e32 v155, v98
	v_pk_add_f32 v[142:143], v[142:143], v[156:157]
	v_pk_mul_f32 v[154:155], v[166:167], v[154:155]
	v_mul_f32_e32 v178, v99, v99
	v_mov_b32_e32 v143, v155
	v_pk_add_f32 v[154:155], v[158:159], v[158:159] op_sel:[0,1] op_sel_hi:[1,0]
	v_mul_f32_e32 v156, v105, v105
	v_mov_b32_e32 v155, v178
	v_pk_add_f32 v[142:143], v[142:143], v[154:155]
	v_mul_f32_e32 v154, v103, v103
	v_mul_f32_e32 v179, v100, v100
	v_mul_f32_e32 v180, v101, v101
	v_pk_fma_f32 v[154:155], v[102:103], v[102:103], v[154:155] op_sel_hi:[1,1,0]
	v_pk_fma_f32 v[156:157], v[104:105], v[104:105], v[156:157] op_sel_hi:[1,1,0]
	v_mov_b32_e32 v155, v179
	v_mov_b32_e32 v157, v180
	v_pk_add_f32 v[154:155], v[154:155], v[156:157]
	s_nop 0
	v_pk_add_f32 v[142:143], v[142:143], v[154:155]
	s_nop 0
	v_add_f32_e32 v142, v142, v143
